# attn work items re-paired as query blocks (63-pp, 31-pp): item sizes descend within each (b,h), smaller items at the queue tail
# speedup vs baseline: 1.0070x; 1.0070x over previous
; template <bool SAMPLE> __device__ __forceinline__ void attn_unit16(const Ctx& c, LAS unsigned char* lds, int b, int h, int qb, int wave_s) {
;     ...
;     if (tid < 256) { const int rel = tid - 128; BT[tid] = (c.rel_bias[t5_bucket(rel) * 8 + h] - c.rel_bias[15 * 8 + h]) * LOG2E; }
.LBB0_888:
	s_mov_b32 s0, -1
	s_waitcnt vmcnt(63) expcnt(7) lgkmcnt(15)
	s_barrier
	s_xor_b32 s56, s56, 31
	s_nop 0
	v_mbcnt_lo_u32_b32 v0, s0, 0
	v_mbcnt_hi_u32_b32 v0, s0, v0
	v_add_u32_e32 v46, s33, v0
	s_nop 0
	v_readfirstlane_b32 s81, v46
	v_cmp_gt_i32_e32 vcc, s66, v46
	s_and_saveexec_b64 s[0:1], vcc
	s_cbranch_execz .LBB0_898
	v_add_u32_e32 v0, 0xffffff80, v46
	v_sub_u32_e32 v2, 0x80, v46
	v_max_i32_e32 v0, v0, v2
	v_cmp_lt_u32_e32 vcc, 7, v0
	s_and_saveexec_b64 s[2:3], vcc
	s_cbranch_execz .LBB0_897
	v_cmp_lt_u32_e32 vcc, 11, v0
	v_mov_b32_e32 v2, 8
	s_and_saveexec_b64 s[50:51], vcc
	s_cbranch_execz .LBB0_896
	v_cmp_lt_u32_e32 vcc, 15, v0
	v_mov_b32_e32 v2, 9
	s_and_saveexec_b64 s[60:61], vcc
	s_cbranch_execz .LBB0_895
	v_cmp_lt_u32_e32 vcc, 22, v0
	v_mov_b32_e32 v2, 10
	s_and_saveexec_b64 s[62:63], vcc
	v_cmp_gt_u32_e32 vcc, s68, v0
	s_nop 1
	v_cndmask_b32_e64 v2, 15, 14, vcc
	v_cmp_lt_u32_e32 vcc, 63, v0
	s_nop 1
	v_cndmask_b32_e32 v2, 13, v2, vcc
	v_cmp_lt_u32_e32 vcc, 45, v0
	s_nop 1
	v_cndmask_b32_e32 v2, 12, v2, vcc
	v_cmp_lt_u32_e32 vcc, 31, v0
	s_nop 1
	v_cndmask_b32_e32 v2, 11, v2, vcc
	s_or_b64 exec, exec, s[62:63]
